# M1 final epilogue: parked-tile loads run two blocks ahead in rotating register sets (epilogue de-serialisation)
# speedup vs baseline: 1.0025x; 1.0025x over previous
; __device__ __forceinline__ float bf_lo(unsigned u) { return __uint_as_float(u << 16); }
; __device__ __forceinline__ float bf_hi(unsigned u) { return __uint_as_float(u & 0xffff0000u); }
; __device__ __forceinline__ int launder_i(int x) { asm volatile("" : "+v"(x)); return x; }
; __device__ void phaseM1(const Params& p, char* lds) {
;     ...
;             } else {
; #pragma unroll
;                 for (int mi = 0; mi < 8; mi++)
; #pragma unroll
;                     for (int nh = 0; nh < 2; nh++) {
;                         const u32x4 sg = SG[(size_t)launder_i(pbase + (mi * 2 + nh) * 512)];
;                         const u32x4 pv = PA[(size_t)launder_i(pbase + (mi * 2 + nh) * 512)];
;                         const f32x4 a0 = acc[mi][2 * nh], a1 = acc[mi][2 * nh + 1];
;                         epi_fill(lds, wr, wc, r, q, mi, 2 * nh, (f32x4){bf_lo(sg.x) * a0[0] + bf_lo(pv.x), bf_hi(sg.x) * a0[1] + bf_hi(pv.x),
;                                                                          bf_lo(sg.y) * a0[2] + bf_lo(pv.y), bf_hi(sg.y) * a0[3] + bf_hi(pv.y)});
;                         epi_fill(lds, wr, wc, r, q, mi, 2 * nh + 1, (f32x4){bf_lo(sg.z) * a1[0] + bf_lo(pv.z), bf_hi(sg.z) * a1[1] + bf_hi(pv.z),
;                                                                              bf_lo(sg.w) * a1[2] + bf_lo(pv.w), bf_hi(sg.w) * a1[3] + bf_hi(pv.w)});
;                     }
.LBB0_719:
	v_mov_b32_e32 v176, v146
	v_ashrrev_i32_e32 v177, 31, v176
	v_lshl_add_u64 v[178:179], v[176:177], 4, s[4:5]
	global_load_dwordx4 v[184:187], v[178:179], off
	v_lshl_add_u64 v[178:179], v[176:177], 4, s[10:11]
	global_load_dwordx4 v[188:191], v[178:179], off
	v_mov_b32_e32 v176, v147
	v_ashrrev_i32_e32 v177, 31, v176
	v_lshl_add_u64 v[178:179], v[176:177], 4, s[4:5]
	global_load_dwordx4 v[192:195], v[178:179], off
	v_lshl_add_u64 v[178:179], v[176:177], 4, s[10:11]
	global_load_dwordx4 v[196:199], v[178:179], off
	v_mov_b32_e32 v176, v148
	v_ashrrev_i32_e32 v177, 31, v176
	v_lshl_add_u64 v[178:179], v[176:177], 4, s[4:5]
	global_load_dwordx4 v[200:203], v[178:179], off
	v_lshl_add_u64 v[178:179], v[176:177], 4, s[10:11]
	global_load_dwordx4 v[204:207], v[178:179], off
	v_add_u32_e32 v128, 0x2000, v145
	v_add_u32_e32 v135, 0xe000, v145
	s_waitcnt vmcnt(4)
	v_lshlrev_b32_e32 v166, 16, v184
	v_and_b32_e32 v167, 0xffff0000, v184
	v_lshlrev_b32_e32 v184, 16, v185
	v_and_b32_e32 v185, 0xffff0000, v185
	v_lshlrev_b32_e32 v168, 16, v186
	v_and_b32_e32 v169, 0xffff0000, v186
	v_lshlrev_b32_e32 v186, 16, v187
	v_and_b32_e32 v187, 0xffff0000, v187
	v_lshlrev_b32_e32 v170, 16, v188
	v_and_b32_e32 v171, 0xffff0000, v188
	v_lshlrev_b32_e32 v188, 16, v189
	v_and_b32_e32 v189, 0xffff0000, v189
	v_lshlrev_b32_e32 v172, 16, v190
	v_and_b32_e32 v173, 0xffff0000, v190
	v_lshlrev_b32_e32 v190, 16, v191
	v_and_b32_e32 v191, 0xffff0000, v191
	v_pk_fma_f32 v[166:167], v[124:125], v[166:167], v[170:171]
	v_pk_fma_f32 v[184:185], v[126:127], v[184:185], v[188:189]
	v_pk_fma_f32 v[188:189], v[120:121], v[168:169], v[172:173]
	v_pk_fma_f32 v[186:187], v[122:123], v[186:187], v[190:191]
	v_cvt_pk_bf16_f32 v190, v166, v167
	v_cvt_pk_bf16_f32 v191, v184, v185
	v_cvt_pk_bf16_f32 v184, v188, v189
	v_cvt_pk_bf16_f32 v185, v186, v187
	ds_write2_b64 v145, v[190:191], v[184:185] offset1:4
	v_mov_b32_e32 v176, v149
	v_ashrrev_i32_e32 v177, 31, v176
	v_lshl_add_u64 v[178:179], v[176:177], 4, s[4:5]
	global_load_dwordx4 v[184:187], v[178:179], off
	v_lshl_add_u64 v[178:179], v[176:177], 4, s[10:11]
	global_load_dwordx4 v[188:191], v[178:179], off
	s_waitcnt vmcnt(4)
	v_lshlrev_b32_e32 v166, 16, v192
	v_and_b32_e32 v167, 0xffff0000, v192
	v_lshlrev_b32_e32 v192, 16, v193
	v_and_b32_e32 v193, 0xffff0000, v193
	v_lshlrev_b32_e32 v168, 16, v194
	v_and_b32_e32 v169, 0xffff0000, v194
	v_lshlrev_b32_e32 v194, 16, v195
	v_and_b32_e32 v195, 0xffff0000, v195
	v_lshlrev_b32_e32 v170, 16, v196
	v_and_b32_e32 v171, 0xffff0000, v196
	v_lshlrev_b32_e32 v196, 16, v197
	v_and_b32_e32 v197, 0xffff0000, v197
	v_lshlrev_b32_e32 v172, 16, v198
	v_and_b32_e32 v173, 0xffff0000, v198
	v_lshlrev_b32_e32 v198, 16, v199
	v_and_b32_e32 v199, 0xffff0000, v199
	v_pk_fma_f32 v[166:167], v[116:117], v[166:167], v[170:171]
	v_pk_fma_f32 v[192:193], v[118:119], v[192:193], v[196:197]
	v_pk_fma_f32 v[196:197], v[112:113], v[168:169], v[172:173]
	v_pk_fma_f32 v[194:195], v[114:115], v[194:195], v[198:199]
	v_cvt_pk_bf16_f32 v198, v166, v167
	v_cvt_pk_bf16_f32 v199, v192, v193
	v_cvt_pk_bf16_f32 v192, v196, v197
	v_cvt_pk_bf16_f32 v193, v194, v195
	ds_write2_b64 v145, v[198:199], v[192:193] offset0:8 offset1:12
	v_mov_b32_e32 v176, v150
	v_ashrrev_i32_e32 v177, 31, v176
	v_lshl_add_u64 v[178:179], v[176:177], 4, s[4:5]
	global_load_dwordx4 v[192:195], v[178:179], off
	v_lshl_add_u64 v[178:179], v[176:177], 4, s[10:11]
	global_load_dwordx4 v[196:199], v[178:179], off
	s_waitcnt vmcnt(4)
	v_lshlrev_b32_e32 v166, 16, v200
	v_and_b32_e32 v167, 0xffff0000, v200
	v_lshlrev_b32_e32 v200, 16, v201
	v_and_b32_e32 v201, 0xffff0000, v201
	v_lshlrev_b32_e32 v168, 16, v202
	v_and_b32_e32 v169, 0xffff0000, v202
	v_lshlrev_b32_e32 v202, 16, v203
	v_and_b32_e32 v203, 0xffff0000, v203
	v_lshlrev_b32_e32 v170, 16, v204
	v_and_b32_e32 v171, 0xffff0000, v204
	v_lshlrev_b32_e32 v204, 16, v205
	v_and_b32_e32 v205, 0xffff0000, v205
	v_lshlrev_b32_e32 v172, 16, v206
	v_and_b32_e32 v173, 0xffff0000, v206
	v_lshlrev_b32_e32 v206, 16, v207
	v_and_b32_e32 v207, 0xffff0000, v207
	v_pk_fma_f32 v[166:167], v[108:109], v[166:167], v[170:171]
	v_pk_fma_f32 v[200:201], v[110:111], v[200:201], v[204:205]
	v_pk_fma_f32 v[204:205], v[104:105], v[168:169], v[172:173]
	v_pk_fma_f32 v[202:203], v[106:107], v[202:203], v[206:207]
	v_cvt_pk_bf16_f32 v206, v166, v167
	v_cvt_pk_bf16_f32 v207, v200, v201
	v_cvt_pk_bf16_f32 v200, v204, v205
	v_cvt_pk_bf16_f32 v201, v202, v203
	ds_write2_b64 v128, v[206:207], v[200:201] offset0:32 offset1:36
	v_mov_b32_e32 v176, v151
	v_ashrrev_i32_e32 v177, 31, v176
	v_lshl_add_u64 v[178:179], v[176:177], 4, s[4:5]
	global_load_dwordx4 v[200:203], v[178:179], off
	v_lshl_add_u64 v[178:179], v[176:177], 4, s[10:11]
	global_load_dwordx4 v[204:207], v[178:179], off
	s_waitcnt vmcnt(4)
	v_lshlrev_b32_e32 v166, 16, v184
	v_and_b32_e32 v167, 0xffff0000, v184
	v_lshlrev_b32_e32 v184, 16, v185
	v_and_b32_e32 v185, 0xffff0000, v185
	v_lshlrev_b32_e32 v168, 16, v186
	v_and_b32_e32 v169, 0xffff0000, v186
	v_lshlrev_b32_e32 v186, 16, v187
	v_and_b32_e32 v187, 0xffff0000, v187
	v_lshlrev_b32_e32 v170, 16, v188
	v_and_b32_e32 v171, 0xffff0000, v188
	v_lshlrev_b32_e32 v188, 16, v189
	v_and_b32_e32 v189, 0xffff0000, v189
	v_lshlrev_b32_e32 v172, 16, v190
	v_and_b32_e32 v173, 0xffff0000, v190
	v_lshlrev_b32_e32 v190, 16, v191
	v_and_b32_e32 v191, 0xffff0000, v191
	v_pk_fma_f32 v[166:167], v[100:101], v[166:167], v[170:171]
	v_pk_fma_f32 v[184:185], v[102:103], v[184:185], v[188:189]
	v_pk_fma_f32 v[188:189], v[96:97], v[168:169], v[172:173]
	v_pk_fma_f32 v[186:187], v[98:99], v[186:187], v[190:191]
	v_cvt_pk_bf16_f32 v190, v166, v167
	v_cvt_pk_bf16_f32 v191, v184, v185
	v_cvt_pk_bf16_f32 v184, v188, v189
	v_cvt_pk_bf16_f32 v185, v186, v187
	ds_write2_b64 v128, v[190:191], v[184:185] offset0:40 offset1:44
	v_mov_b32_e32 v176, v152
	v_ashrrev_i32_e32 v177, 31, v176
	v_lshl_add_u64 v[178:179], v[176:177], 4, s[4:5]
	global_load_dwordx4 v[184:187], v[178:179], off
	v_lshl_add_u64 v[178:179], v[176:177], 4, s[10:11]
	global_load_dwordx4 v[188:191], v[178:179], off
	v_add_u32_e32 v128, 0x4000, v145
	s_waitcnt vmcnt(4)
; __device__ __forceinline__ float bf_lo(unsigned u) { return __uint_as_float(u << 16); }
; __device__ __forceinline__ float bf_hi(unsigned u) { return __uint_as_float(u & 0xffff0000u); }
; __device__ __forceinline__ int launder_i(int x) { asm volatile("" : "+v"(x)); return x; }
; __device__ void phaseM1(const Params& p, char* lds) {
;     ...
;             } else {
; #pragma unroll
;                 for (int mi = 0; mi < 8; mi++)
; #pragma unroll
;                     for (int nh = 0; nh < 2; nh++) {
;                         const u32x4 sg = SG[(size_t)launder_i(pbase + (mi * 2 + nh) * 512)];
;                         const u32x4 pv = PA[(size_t)launder_i(pbase + (mi * 2 + nh) * 512)];
;                         const f32x4 a0 = acc[mi][2 * nh], a1 = acc[mi][2 * nh + 1];
;                         epi_fill(lds, wr, wc, r, q, mi, 2 * nh, (f32x4){bf_lo(sg.x) * a0[0] + bf_lo(pv.x), bf_hi(sg.x) * a0[1] + bf_hi(pv.x),
;                                                                          bf_lo(sg.y) * a0[2] + bf_lo(pv.y), bf_hi(sg.y) * a0[3] + bf_hi(pv.y)});
;                         epi_fill(lds, wr, wc, r, q, mi, 2 * nh + 1, (f32x4){bf_lo(sg.z) * a1[0] + bf_lo(pv.z), bf_hi(sg.z) * a1[1] + bf_hi(pv.z),
;                                                                              bf_lo(sg.w) * a1[2] + bf_lo(pv.w), bf_hi(sg.w) * a1[3] + bf_hi(pv.w)});
;                     }
	v_lshlrev_b32_e32 v166, 16, v192
	v_and_b32_e32 v167, 0xffff0000, v192
	v_lshlrev_b32_e32 v192, 16, v193
	v_and_b32_e32 v193, 0xffff0000, v193
	v_lshlrev_b32_e32 v168, 16, v194
	v_and_b32_e32 v169, 0xffff0000, v194
	v_lshlrev_b32_e32 v194, 16, v195
	v_and_b32_e32 v195, 0xffff0000, v195
	v_lshlrev_b32_e32 v170, 16, v196
	v_and_b32_e32 v171, 0xffff0000, v196
	v_lshlrev_b32_e32 v196, 16, v197
	v_and_b32_e32 v197, 0xffff0000, v197
	v_lshlrev_b32_e32 v172, 16, v198
	v_and_b32_e32 v173, 0xffff0000, v198
	v_lshlrev_b32_e32 v198, 16, v199
	v_and_b32_e32 v199, 0xffff0000, v199
	v_pk_fma_f32 v[166:167], v[92:93], v[166:167], v[170:171]
	v_pk_fma_f32 v[192:193], v[94:95], v[192:193], v[196:197]
	v_pk_fma_f32 v[196:197], v[88:89], v[168:169], v[172:173]
	v_pk_fma_f32 v[194:195], v[90:91], v[194:195], v[198:199]
	v_cvt_pk_bf16_f32 v198, v166, v167
	v_cvt_pk_bf16_f32 v199, v192, v193
	v_cvt_pk_bf16_f32 v192, v196, v197
	v_cvt_pk_bf16_f32 v193, v194, v195
	ds_write2_b64 v128, v[198:199], v[192:193] offset0:64 offset1:68
	v_mov_b32_e32 v176, v153
	v_ashrrev_i32_e32 v177, 31, v176
	v_lshl_add_u64 v[178:179], v[176:177], 4, s[4:5]
	global_load_dwordx4 v[192:195], v[178:179], off
	v_lshl_add_u64 v[178:179], v[176:177], 4, s[10:11]
	global_load_dwordx4 v[196:199], v[178:179], off
	s_waitcnt vmcnt(4)
	v_lshlrev_b32_e32 v166, 16, v200
	v_and_b32_e32 v167, 0xffff0000, v200
	v_lshlrev_b32_e32 v200, 16, v201
	v_and_b32_e32 v201, 0xffff0000, v201
	v_lshlrev_b32_e32 v168, 16, v202
	v_and_b32_e32 v169, 0xffff0000, v202
	v_lshlrev_b32_e32 v202, 16, v203
	v_and_b32_e32 v203, 0xffff0000, v203
	v_lshlrev_b32_e32 v170, 16, v204
	v_and_b32_e32 v171, 0xffff0000, v204
	v_lshlrev_b32_e32 v204, 16, v205
	v_and_b32_e32 v205, 0xffff0000, v205
	v_lshlrev_b32_e32 v172, 16, v206
	v_and_b32_e32 v173, 0xffff0000, v206
	v_lshlrev_b32_e32 v206, 16, v207
	v_and_b32_e32 v207, 0xffff0000, v207
	v_pk_fma_f32 v[166:167], v[84:85], v[166:167], v[170:171]
	v_pk_fma_f32 v[200:201], v[86:87], v[200:201], v[204:205]
	v_pk_fma_f32 v[204:205], v[80:81], v[168:169], v[172:173]
	v_pk_fma_f32 v[202:203], v[82:83], v[202:203], v[206:207]
	v_cvt_pk_bf16_f32 v206, v166, v167
	v_cvt_pk_bf16_f32 v207, v200, v201
	v_cvt_pk_bf16_f32 v200, v204, v205
	v_cvt_pk_bf16_f32 v201, v202, v203
	ds_write2_b64 v128, v[206:207], v[200:201] offset0:72 offset1:76
	v_mov_b32_e32 v176, v154
	v_ashrrev_i32_e32 v177, 31, v176
	v_lshl_add_u64 v[178:179], v[176:177], 4, s[4:5]
	global_load_dwordx4 v[200:203], v[178:179], off
	v_lshl_add_u64 v[178:179], v[176:177], 4, s[10:11]
	global_load_dwordx4 v[204:207], v[178:179], off
	v_add_u32_e32 v128, 0x6000, v145
	s_waitcnt vmcnt(4)
	v_lshlrev_b32_e32 v166, 16, v184
	v_and_b32_e32 v167, 0xffff0000, v184
	v_lshlrev_b32_e32 v184, 16, v185
	v_and_b32_e32 v185, 0xffff0000, v185
	v_lshlrev_b32_e32 v168, 16, v186
	v_and_b32_e32 v169, 0xffff0000, v186
	v_lshlrev_b32_e32 v186, 16, v187
	v_and_b32_e32 v187, 0xffff0000, v187
	v_lshlrev_b32_e32 v170, 16, v188
	v_and_b32_e32 v171, 0xffff0000, v188
	v_lshlrev_b32_e32 v188, 16, v189
	v_and_b32_e32 v189, 0xffff0000, v189
	v_lshlrev_b32_e32 v172, 16, v190
	v_and_b32_e32 v173, 0xffff0000, v190
	v_lshlrev_b32_e32 v190, 16, v191
	v_and_b32_e32 v191, 0xffff0000, v191
	v_pk_fma_f32 v[166:167], v[76:77], v[166:167], v[170:171]
	v_pk_fma_f32 v[184:185], v[78:79], v[184:185], v[188:189]
	v_pk_fma_f32 v[188:189], v[72:73], v[168:169], v[172:173]
	v_pk_fma_f32 v[186:187], v[74:75], v[186:187], v[190:191]
	v_cvt_pk_bf16_f32 v190, v166, v167
	v_cvt_pk_bf16_f32 v191, v184, v185
	v_cvt_pk_bf16_f32 v184, v188, v189
	v_cvt_pk_bf16_f32 v185, v186, v187
	ds_write2_b64 v128, v[190:191], v[184:185] offset0:96 offset1:100
	v_mov_b32_e32 v176, v155
	v_ashrrev_i32_e32 v177, 31, v176
	v_lshl_add_u64 v[178:179], v[176:177], 4, s[4:5]
	global_load_dwordx4 v[184:187], v[178:179], off
	v_lshl_add_u64 v[178:179], v[176:177], 4, s[10:11]
	global_load_dwordx4 v[188:191], v[178:179], off
	s_waitcnt vmcnt(4)
	v_lshlrev_b32_e32 v166, 16, v192
	v_and_b32_e32 v167, 0xffff0000, v192
	v_lshlrev_b32_e32 v192, 16, v193
	v_and_b32_e32 v193, 0xffff0000, v193
	v_lshlrev_b32_e32 v168, 16, v194
	v_and_b32_e32 v169, 0xffff0000, v194
	v_lshlrev_b32_e32 v194, 16, v195
	v_and_b32_e32 v195, 0xffff0000, v195
	v_lshlrev_b32_e32 v170, 16, v196
	v_and_b32_e32 v171, 0xffff0000, v196
	v_lshlrev_b32_e32 v196, 16, v197
	v_and_b32_e32 v197, 0xffff0000, v197
	v_lshlrev_b32_e32 v172, 16, v198
	v_and_b32_e32 v173, 0xffff0000, v198
	v_lshlrev_b32_e32 v198, 16, v199
	v_and_b32_e32 v199, 0xffff0000, v199
	v_pk_fma_f32 v[166:167], v[64:65], v[166:167], v[170:171]
	v_pk_fma_f32 v[192:193], v[66:67], v[192:193], v[196:197]
	v_pk_fma_f32 v[196:197], v[68:69], v[168:169], v[172:173]
	v_pk_fma_f32 v[194:195], v[70:71], v[194:195], v[198:199]
	v_cvt_pk_bf16_f32 v198, v166, v167
	v_cvt_pk_bf16_f32 v199, v192, v193
	v_cvt_pk_bf16_f32 v192, v196, v197
	v_cvt_pk_bf16_f32 v193, v194, v195
	ds_write2_b64 v128, v[198:199], v[192:193] offset0:104 offset1:108
	v_mov_b32_e32 v176, v156
	v_ashrrev_i32_e32 v177, 31, v176
	v_lshl_add_u64 v[178:179], v[176:177], 4, s[4:5]
	global_load_dwordx4 v[192:195], v[178:179], off
	v_lshl_add_u64 v[178:179], v[176:177], 4, s[10:11]
	global_load_dwordx4 v[196:199], v[178:179], off
	v_add_u32_e32 v128, 0x8000, v145
	s_waitcnt vmcnt(4)
; __device__ __forceinline__ float bf_lo(unsigned u) { return __uint_as_float(u << 16); }
; __device__ __forceinline__ float bf_hi(unsigned u) { return __uint_as_float(u & 0xffff0000u); }
; __device__ __forceinline__ int launder_i(int x) { asm volatile("" : "+v"(x)); return x; }
; __device__ void phaseM1(const Params& p, char* lds) {
;     ...
;             } else {
; #pragma unroll
;                 for (int mi = 0; mi < 8; mi++)
; #pragma unroll
;                     for (int nh = 0; nh < 2; nh++) {
;                         const u32x4 sg = SG[(size_t)launder_i(pbase + (mi * 2 + nh) * 512)];
;                         const u32x4 pv = PA[(size_t)launder_i(pbase + (mi * 2 + nh) * 512)];
;                         const f32x4 a0 = acc[mi][2 * nh], a1 = acc[mi][2 * nh + 1];
;                         epi_fill(lds, wr, wc, r, q, mi, 2 * nh, (f32x4){bf_lo(sg.x) * a0[0] + bf_lo(pv.x), bf_hi(sg.x) * a0[1] + bf_hi(pv.x),
;                                                                          bf_lo(sg.y) * a0[2] + bf_lo(pv.y), bf_hi(sg.y) * a0[3] + bf_hi(pv.y)});
;                         epi_fill(lds, wr, wc, r, q, mi, 2 * nh + 1, (f32x4){bf_lo(sg.z) * a1[0] + bf_lo(pv.z), bf_hi(sg.z) * a1[1] + bf_hi(pv.z),
;                                                                              bf_lo(sg.w) * a1[2] + bf_lo(pv.w), bf_hi(sg.w) * a1[3] + bf_hi(pv.w)});
;                     }
	v_lshlrev_b32_e32 v166, 16, v200
	v_and_b32_e32 v167, 0xffff0000, v200
	v_lshlrev_b32_e32 v200, 16, v201
	v_and_b32_e32 v201, 0xffff0000, v201
	v_lshlrev_b32_e32 v168, 16, v202
	v_and_b32_e32 v169, 0xffff0000, v202
	v_lshlrev_b32_e32 v202, 16, v203
	v_and_b32_e32 v203, 0xffff0000, v203
	v_lshlrev_b32_e32 v170, 16, v204
	v_and_b32_e32 v171, 0xffff0000, v204
	v_lshlrev_b32_e32 v204, 16, v205
	v_and_b32_e32 v205, 0xffff0000, v205
	v_lshlrev_b32_e32 v172, 16, v206
	v_and_b32_e32 v173, 0xffff0000, v206
	v_lshlrev_b32_e32 v206, 16, v207
	v_and_b32_e32 v207, 0xffff0000, v207
	v_pk_fma_f32 v[166:167], v[60:61], v[166:167], v[170:171]
	v_pk_fma_f32 v[200:201], v[62:63], v[200:201], v[204:205]
	v_pk_fma_f32 v[204:205], v[56:57], v[168:169], v[172:173]
	v_pk_fma_f32 v[202:203], v[58:59], v[202:203], v[206:207]
	v_cvt_pk_bf16_f32 v206, v166, v167
	v_cvt_pk_bf16_f32 v207, v200, v201
	v_cvt_pk_bf16_f32 v200, v204, v205
	v_cvt_pk_bf16_f32 v201, v202, v203
	ds_write2_b64 v128, v[206:207], v[200:201] offset0:128 offset1:132
	v_mov_b32_e32 v176, v157
	v_ashrrev_i32_e32 v177, 31, v176
	v_lshl_add_u64 v[178:179], v[176:177], 4, s[4:5]
	global_load_dwordx4 v[200:203], v[178:179], off
	v_lshl_add_u64 v[178:179], v[176:177], 4, s[10:11]
	global_load_dwordx4 v[204:207], v[178:179], off
	s_waitcnt vmcnt(4)
	v_lshlrev_b32_e32 v166, 16, v184
	v_and_b32_e32 v167, 0xffff0000, v184
	v_lshlrev_b32_e32 v184, 16, v185
	v_and_b32_e32 v185, 0xffff0000, v185
	v_lshlrev_b32_e32 v168, 16, v186
	v_and_b32_e32 v169, 0xffff0000, v186
	v_lshlrev_b32_e32 v186, 16, v187
	v_and_b32_e32 v187, 0xffff0000, v187
	v_lshlrev_b32_e32 v170, 16, v188
	v_and_b32_e32 v171, 0xffff0000, v188
	v_lshlrev_b32_e32 v188, 16, v189
	v_and_b32_e32 v189, 0xffff0000, v189
	v_lshlrev_b32_e32 v172, 16, v190
	v_and_b32_e32 v173, 0xffff0000, v190
	v_lshlrev_b32_e32 v190, 16, v191
	v_and_b32_e32 v191, 0xffff0000, v191
	v_pk_fma_f32 v[166:167], v[52:53], v[166:167], v[170:171]
	v_pk_fma_f32 v[184:185], v[54:55], v[184:185], v[188:189]
	v_pk_fma_f32 v[188:189], v[48:49], v[168:169], v[172:173]
	v_pk_fma_f32 v[186:187], v[50:51], v[186:187], v[190:191]
	v_cvt_pk_bf16_f32 v190, v166, v167
	v_cvt_pk_bf16_f32 v191, v184, v185
	v_cvt_pk_bf16_f32 v184, v188, v189
	v_cvt_pk_bf16_f32 v185, v186, v187
	ds_write2_b64 v128, v[190:191], v[184:185] offset0:136 offset1:140
	v_mov_b32_e32 v176, v160
	v_ashrrev_i32_e32 v177, 31, v176
	v_lshl_add_u64 v[178:179], v[176:177], 4, s[4:5]
	global_load_dwordx4 v[184:187], v[178:179], off
	v_lshl_add_u64 v[178:179], v[176:177], 4, s[10:11]
	global_load_dwordx4 v[188:191], v[178:179], off
	v_add_u32_e32 v128, 0xa000, v145
	s_waitcnt vmcnt(4)
	v_lshlrev_b32_e32 v166, 16, v192
	v_and_b32_e32 v167, 0xffff0000, v192
	v_lshlrev_b32_e32 v192, 16, v193
	v_and_b32_e32 v193, 0xffff0000, v193
	v_lshlrev_b32_e32 v168, 16, v194
	v_and_b32_e32 v169, 0xffff0000, v194
	v_lshlrev_b32_e32 v194, 16, v195
	v_and_b32_e32 v195, 0xffff0000, v195
	v_lshlrev_b32_e32 v170, 16, v196
	v_and_b32_e32 v171, 0xffff0000, v196
	v_lshlrev_b32_e32 v196, 16, v197
	v_and_b32_e32 v197, 0xffff0000, v197
	v_lshlrev_b32_e32 v172, 16, v198
	v_and_b32_e32 v173, 0xffff0000, v198
	v_lshlrev_b32_e32 v198, 16, v199
	v_and_b32_e32 v199, 0xffff0000, v199
	v_pk_fma_f32 v[166:167], v[44:45], v[166:167], v[170:171]
	v_pk_fma_f32 v[192:193], v[46:47], v[192:193], v[196:197]
	v_pk_fma_f32 v[196:197], v[40:41], v[168:169], v[172:173]
	v_pk_fma_f32 v[194:195], v[42:43], v[194:195], v[198:199]
	v_cvt_pk_bf16_f32 v198, v166, v167
	v_cvt_pk_bf16_f32 v199, v192, v193
	v_cvt_pk_bf16_f32 v192, v196, v197
	v_cvt_pk_bf16_f32 v193, v194, v195
	ds_write2_b64 v128, v[198:199], v[192:193] offset0:160 offset1:164
	v_mov_b32_e32 v176, v161
	v_ashrrev_i32_e32 v177, 31, v176
	v_lshl_add_u64 v[178:179], v[176:177], 4, s[4:5]
	global_load_dwordx4 v[192:195], v[178:179], off
	v_lshl_add_u64 v[178:179], v[176:177], 4, s[10:11]
	global_load_dwordx4 v[196:199], v[178:179], off
	s_waitcnt vmcnt(4)
	v_lshlrev_b32_e32 v166, 16, v200
	v_and_b32_e32 v167, 0xffff0000, v200
	v_lshlrev_b32_e32 v200, 16, v201
	v_and_b32_e32 v201, 0xffff0000, v201
	v_lshlrev_b32_e32 v168, 16, v202
	v_and_b32_e32 v169, 0xffff0000, v202
	v_lshlrev_b32_e32 v202, 16, v203
	v_and_b32_e32 v203, 0xffff0000, v203
	v_lshlrev_b32_e32 v170, 16, v204
	v_and_b32_e32 v171, 0xffff0000, v204
	v_lshlrev_b32_e32 v204, 16, v205
	v_and_b32_e32 v205, 0xffff0000, v205
	v_lshlrev_b32_e32 v172, 16, v206
	v_and_b32_e32 v173, 0xffff0000, v206
	v_lshlrev_b32_e32 v206, 16, v207
	v_and_b32_e32 v207, 0xffff0000, v207
	v_pk_fma_f32 v[166:167], v[36:37], v[166:167], v[170:171]
	v_pk_fma_f32 v[200:201], v[38:39], v[200:201], v[204:205]
	v_pk_fma_f32 v[204:205], v[32:33], v[168:169], v[172:173]
	v_pk_fma_f32 v[202:203], v[34:35], v[202:203], v[206:207]
	v_cvt_pk_bf16_f32 v206, v166, v167
	v_cvt_pk_bf16_f32 v207, v200, v201
	v_cvt_pk_bf16_f32 v200, v204, v205
	v_cvt_pk_bf16_f32 v201, v202, v203
	ds_write2_b64 v128, v[206:207], v[200:201] offset0:168 offset1:172
	v_mov_b32_e32 v176, v162
	v_ashrrev_i32_e32 v177, 31, v176
	v_lshl_add_u64 v[178:179], v[176:177], 4, s[4:5]
	global_load_dwordx4 v[200:203], v[178:179], off
	v_lshl_add_u64 v[178:179], v[176:177], 4, s[10:11]
	global_load_dwordx4 v[204:207], v[178:179], off
	v_add_u32_e32 v128, 0xc000, v145
	s_waitcnt vmcnt(4)
; __device__ __forceinline__ float bf_lo(unsigned u) { return __uint_as_float(u << 16); }
; __device__ __forceinline__ float bf_hi(unsigned u) { return __uint_as_float(u & 0xffff0000u); }
; __device__ __forceinline__ int launder_i(int x) { asm volatile("" : "+v"(x)); return x; }
; #define TIDX512 launder_i((int)threadIdx.x)
; __device__ __forceinline__ void epi_store(const char* lds, bf16_t* __restrict__ O, int ldo, int m0, int n0, int ncols_valid) {
;     const int t = TIDX512;
;     const int chunk = t & 31, rsub = t >> 5;
;     if (n0 + chunk * 8 < ncols_valid) {
; __device__ void phaseM1(const Params& p, char* lds) {
;     ...
;                     for (int nh = 0; nh < 2; nh++) {
;                         const u32x4 sg = SG[(size_t)launder_i(pbase + (mi * 2 + nh) * 512)];
;                         const u32x4 pv = PA[(size_t)launder_i(pbase + (mi * 2 + nh) * 512)];
;                         const f32x4 a0 = acc[mi][2 * nh], a1 = acc[mi][2 * nh + 1];
;                         epi_fill(lds, wr, wc, r, q, mi, 2 * nh, (f32x4){bf_lo(sg.x) * a0[0] + bf_lo(pv.x), bf_hi(sg.x) * a0[1] + bf_hi(pv.x),
;                                                                          bf_lo(sg.y) * a0[2] + bf_lo(pv.y), bf_hi(sg.y) * a0[3] + bf_hi(pv.y)});
;                         epi_fill(lds, wr, wc, r, q, mi, 2 * nh + 1, (f32x4){bf_lo(sg.z) * a1[0] + bf_lo(pv.z), bf_hi(sg.z) * a1[1] + bf_hi(pv.z),
;                                                                              bf_lo(sg.w) * a1[2] + bf_lo(pv.w), bf_hi(sg.w) * a1[3] + bf_hi(pv.w)});
;                     }
;                 __syncthreads();
	v_lshlrev_b32_e32 v166, 16, v184
	v_and_b32_e32 v167, 0xffff0000, v184
	v_lshlrev_b32_e32 v184, 16, v185
	v_and_b32_e32 v185, 0xffff0000, v185
	v_lshlrev_b32_e32 v168, 16, v186
	v_and_b32_e32 v169, 0xffff0000, v186
	v_lshlrev_b32_e32 v186, 16, v187
	v_and_b32_e32 v187, 0xffff0000, v187
	v_lshlrev_b32_e32 v170, 16, v188
	v_and_b32_e32 v171, 0xffff0000, v188
	v_lshlrev_b32_e32 v188, 16, v189
	v_and_b32_e32 v189, 0xffff0000, v189
	v_lshlrev_b32_e32 v172, 16, v190
	v_and_b32_e32 v173, 0xffff0000, v190
	v_lshlrev_b32_e32 v190, 16, v191
	v_and_b32_e32 v191, 0xffff0000, v191
	v_pk_fma_f32 v[166:167], v[28:29], v[166:167], v[170:171]
	v_pk_fma_f32 v[184:185], v[30:31], v[184:185], v[188:189]
	v_pk_fma_f32 v[188:189], v[24:25], v[168:169], v[172:173]
	v_pk_fma_f32 v[186:187], v[26:27], v[186:187], v[190:191]
	v_cvt_pk_bf16_f32 v190, v166, v167
	v_cvt_pk_bf16_f32 v191, v184, v185
	v_cvt_pk_bf16_f32 v184, v188, v189
	v_cvt_pk_bf16_f32 v185, v186, v187
	ds_write2_b64 v128, v[190:191], v[184:185] offset0:192 offset1:196
	v_mov_b32_e32 v176, v163
	v_ashrrev_i32_e32 v177, 31, v176
	v_lshl_add_u64 v[178:179], v[176:177], 4, s[4:5]
	global_load_dwordx4 v[184:187], v[178:179], off
	v_lshl_add_u64 v[178:179], v[176:177], 4, s[10:11]
	global_load_dwordx4 v[188:191], v[178:179], off
	s_waitcnt vmcnt(4)
	v_lshlrev_b32_e32 v166, 16, v192
	v_and_b32_e32 v167, 0xffff0000, v192
	v_lshlrev_b32_e32 v192, 16, v193
	v_and_b32_e32 v193, 0xffff0000, v193
	v_lshlrev_b32_e32 v168, 16, v194
	v_and_b32_e32 v169, 0xffff0000, v194
	v_lshlrev_b32_e32 v194, 16, v195
	v_and_b32_e32 v195, 0xffff0000, v195
	v_lshlrev_b32_e32 v170, 16, v196
	v_and_b32_e32 v171, 0xffff0000, v196
	v_lshlrev_b32_e32 v196, 16, v197
	v_and_b32_e32 v197, 0xffff0000, v197
	v_lshlrev_b32_e32 v172, 16, v198
	v_and_b32_e32 v173, 0xffff0000, v198
	v_lshlrev_b32_e32 v198, 16, v199
	v_and_b32_e32 v199, 0xffff0000, v199
	v_pk_fma_f32 v[166:167], v[20:21], v[166:167], v[170:171]
	v_pk_fma_f32 v[192:193], v[22:23], v[192:193], v[196:197]
	v_pk_fma_f32 v[196:197], v[16:17], v[168:169], v[172:173]
	v_pk_fma_f32 v[194:195], v[18:19], v[194:195], v[198:199]
	v_cvt_pk_bf16_f32 v198, v166, v167
	v_cvt_pk_bf16_f32 v199, v192, v193
	v_cvt_pk_bf16_f32 v192, v196, v197
	v_cvt_pk_bf16_f32 v193, v194, v195
	ds_write2_b64 v128, v[198:199], v[192:193] offset0:200 offset1:204
	v_mov_b32_e32 v128, v158
	s_waitcnt vmcnt(2)
	v_lshlrev_b32_e32 v166, 16, v200
	v_and_b32_e32 v167, 0xffff0000, v200
	v_lshlrev_b32_e32 v200, 16, v201
	v_and_b32_e32 v201, 0xffff0000, v201
	v_lshlrev_b32_e32 v168, 16, v202
	v_and_b32_e32 v169, 0xffff0000, v202
	v_lshlrev_b32_e32 v202, 16, v203
	v_and_b32_e32 v203, 0xffff0000, v203
	v_lshlrev_b32_e32 v170, 16, v204
	v_and_b32_e32 v171, 0xffff0000, v204
	v_lshlrev_b32_e32 v204, 16, v205
	v_and_b32_e32 v205, 0xffff0000, v205
	v_lshlrev_b32_e32 v172, 16, v206
	v_and_b32_e32 v173, 0xffff0000, v206
	v_lshlrev_b32_e32 v206, 16, v207
	v_and_b32_e32 v207, 0xffff0000, v207
	v_pk_fma_f32 v[166:167], v[12:13], v[166:167], v[170:171]
	v_pk_fma_f32 v[200:201], v[14:15], v[200:201], v[204:205]
	v_pk_fma_f32 v[204:205], v[8:9], v[168:169], v[172:173]
	v_pk_fma_f32 v[202:203], v[10:11], v[202:203], v[206:207]
	v_cvt_pk_bf16_f32 v206, v166, v167
	v_cvt_pk_bf16_f32 v207, v200, v201
	v_cvt_pk_bf16_f32 v200, v204, v205
	v_cvt_pk_bf16_f32 v201, v202, v203
	ds_write2_b64 v135, v[206:207], v[200:201] offset0:224 offset1:228
	s_waitcnt vmcnt(0)
	v_lshlrev_b32_e32 v164, 16, v184
	v_and_b32_e32 v165, 0xffff0000, v184
	v_lshlrev_b32_e32 v184, 16, v185
	v_and_b32_e32 v185, 0xffff0000, v185
	v_lshlrev_b32_e32 v166, 16, v186
	v_and_b32_e32 v167, 0xffff0000, v186
	v_lshlrev_b32_e32 v186, 16, v187
	v_and_b32_e32 v187, 0xffff0000, v187
	v_lshlrev_b32_e32 v168, 16, v188
	v_and_b32_e32 v169, 0xffff0000, v188
	v_lshlrev_b32_e32 v188, 16, v189
	v_and_b32_e32 v189, 0xffff0000, v189
	v_lshlrev_b32_e32 v170, 16, v190
	v_and_b32_e32 v171, 0xffff0000, v190
	v_lshlrev_b32_e32 v190, 16, v191
	v_and_b32_e32 v191, 0xffff0000, v191
	v_pk_fma_f32 v[164:165], v[4:5], v[164:165], v[168:169]
	v_pk_fma_f32 v[184:185], v[6:7], v[184:185], v[188:189]
	v_pk_fma_f32 v[188:189], v[0:1], v[166:167], v[170:171]
	v_pk_fma_f32 v[186:187], v[2:3], v[186:187], v[190:191]
	v_cvt_pk_bf16_f32 v190, v164, v165
	v_cvt_pk_bf16_f32 v191, v184, v185
	v_cvt_pk_bf16_f32 v184, v188, v189
	v_cvt_pk_bf16_f32 v185, v186, v187
	ds_write2_b64 v135, v[190:191], v[184:185] offset0:232 offset1:236
	s_waitcnt lgkmcnt(0)
	s_barrier
	s_nop 0
	v_and_b32_e32 v135, 31, v128
	v_lshlrev_b32_e32 v136, 3, v135
	v_or_b32_e32 v137, s48, v136
	v_cmp_gt_i32_e32 vcc, s66, v137
	s_and_saveexec_b64 s[54:55], vcc
	s_cbranch_execz .LBB0_721
; #define TIDX512 launder_i((int)threadIdx.x)
; __device__ __forceinline__ void epi_store(const char* lds, bf16_t* __restrict__ O, int ldo, int m0, int n0, int ncols_valid) {
;     const int t = TIDX512;
;     const int chunk = t & 31, rsub = t >> 5;
;     if (n0 + chunk * 8 < ncols_valid) {
; #pragma unroll
;         for (int ps = 0; ps < 16; ps++) {
;             const int row = ps * 16 + rsub;
;             const u32x4 v = *(const u32x4*)(lds + row * EPI_ROWB + chunk * 16);
;             *(u32x4*)(O + (size_t)(m0 + row) * ldo + n0 + chunk * 8) = v;
;         }
;     }
	v_ashrrev_i32_e32 v140, 5, v128
	v_lshlrev_b32_e32 v128, 1, v136
	v_lshl_add_u64 v[164:165], s[50:51], 0, v[128:129]
	v_mul_lo_u32 v128, v140, s62
	v_lshl_add_u32 v128, v135, 4, v128
	ds_read_b128 v[136:139], v128
	v_add_u32_e32 v166, s74, v140
	v_ashrrev_i32_e32 v167, 31, v166
	v_lshlrev_b64 v[140:141], 11, v[166:167]
	v_lshl_add_u64 v[168:169], v[164:165], 0, v[140:141]
	ds_read_b128 v[140:143], v128 offset:8448
	s_waitcnt lgkmcnt(1)
	global_store_dwordx4 v[168:169], v[136:139], off
	v_add_u32_e32 v135, 0x2100, v128
	v_add_u32_e32 v167, 0x4200, v128
	v_add_u32_e32 v136, 16, v166
	v_ashrrev_i32_e32 v137, 31, v136
	v_lshlrev_b64 v[136:137], 11, v[136:137]
	v_lshl_add_u64 v[136:137], v[164:165], 0, v[136:137]
	s_waitcnt lgkmcnt(0)
	global_store_dwordx4 v[136:137], v[140:143], off
	ds_read_b128 v[136:139], v128 offset:16896
	v_add_u32_e32 v170, 0x6300, v128
	v_add_u32_e32 v140, 32, v166
	v_ashrrev_i32_e32 v141, 31, v140
	v_lshlrev_b64 v[140:141], 11, v[140:141]
	v_lshl_add_u64 v[168:169], v[164:165], 0, v[140:141]
	ds_read_b128 v[140:143], v128 offset:25344
	s_waitcnt lgkmcnt(1)
	global_store_dwordx4 v[168:169], v[136:139], off
	v_add_u32_e32 v171, 0x8400, v128
	v_add_u32_e32 v172, 0xa500, v128
	v_add_u32_e32 v136, 48, v166
	v_ashrrev_i32_e32 v137, 31, v136
	v_lshlrev_b64 v[136:137], 11, v[136:137]
	v_lshl_add_u64 v[136:137], v[164:165], 0, v[136:137]
	s_waitcnt lgkmcnt(0)
	global_store_dwordx4 v[136:137], v[140:143], off
	ds_read_b128 v[136:139], v128 offset:33792
	v_add_u32_e32 v173, 0xc600, v128
	v_add_u32_e32 v140, 64, v166
	v_ashrrev_i32_e32 v141, 31, v140
	v_lshlrev_b64 v[140:141], 11, v[140:141]
	v_lshl_add_u64 v[168:169], v[164:165], 0, v[140:141]
	ds_read_b128 v[140:143], v128 offset:42240
	s_waitcnt lgkmcnt(1)
	global_store_dwordx4 v[168:169], v[136:139], off
	v_add_u32_e32 v174, 0xe700, v135
	s_nop 0
	v_add_u32_e32 v136, 0x50, v166
	v_ashrrev_i32_e32 v137, 31, v136
	v_lshlrev_b64 v[136:137], 11, v[136:137]
	v_lshl_add_u64 v[136:137], v[164:165], 0, v[136:137]
	s_waitcnt lgkmcnt(0)
	global_store_dwordx4 v[136:137], v[140:143], off
	ds_read_b128 v[136:139], v128 offset:50688
	s_nop 0
	v_add_u32_e32 v140, 0x60, v166
	v_ashrrev_i32_e32 v141, 31, v140
	v_lshlrev_b64 v[140:141], 11, v[140:141]
	v_lshl_add_u64 v[168:169], v[164:165], 0, v[140:141]
	ds_read_b128 v[140:143], v128 offset:59136
	s_waitcnt lgkmcnt(1)
	global_store_dwordx4 v[168:169], v[136:139], off
	v_add_u32_e32 v128, 0xe700, v128
	s_nop 0
	v_add_u32_e32 v136, 0x70, v166
	v_ashrrev_i32_e32 v137, 31, v136
	v_lshlrev_b64 v[136:137], 11, v[136:137]
	v_lshl_add_u64 v[136:137], v[164:165], 0, v[136:137]
	s_waitcnt lgkmcnt(0)
	global_store_dwordx4 v[136:137], v[140:143], off
	ds_read_b128 v[136:139], v135 offset:59136
	s_nop 0
	v_add_u32_e32 v140, 0x80, v166
	v_ashrrev_i32_e32 v141, 31, v140
	v_lshlrev_b64 v[140:141], 11, v[140:141]
	v_lshl_add_u64 v[168:169], v[164:165], 0, v[140:141]
	ds_read_b128 v[140:143], v167 offset:59136
	s_waitcnt lgkmcnt(1)
	global_store_dwordx4 v[168:169], v[136:139], off
	s_nop 1
	v_add_u32_e32 v136, 0x90, v166
	v_ashrrev_i32_e32 v137, 31, v136
	v_lshlrev_b64 v[136:137], 11, v[136:137]
	v_lshl_add_u64 v[136:137], v[164:165], 0, v[136:137]
	s_waitcnt lgkmcnt(0)
	global_store_dwordx4 v[136:137], v[140:143], off
	ds_read_b128 v[136:139], v170 offset:59136
	s_nop 0
	v_add_u32_e32 v140, 0xa0, v166
	v_ashrrev_i32_e32 v141, 31, v140
	v_lshlrev_b64 v[140:141], 11, v[140:141]
	v_lshl_add_u64 v[168:169], v[164:165], 0, v[140:141]
	ds_read_b128 v[140:143], v171 offset:59136
	s_waitcnt lgkmcnt(1)
	global_store_dwordx4 v[168:169], v[136:139], off
	s_nop 1
	v_add_u32_e32 v136, 0xb0, v166
	v_ashrrev_i32_e32 v137, 31, v136
	v_lshlrev_b64 v[136:137], 11, v[136:137]
	v_lshl_add_u64 v[136:137], v[164:165], 0, v[136:137]
	s_waitcnt lgkmcnt(0)
	global_store_dwordx4 v[136:137], v[140:143], off
	ds_read_b128 v[136:139], v172 offset:59136
	s_nop 0
	v_add_u32_e32 v140, 0xc0, v166
	v_ashrrev_i32_e32 v141, 31, v140
	v_lshlrev_b64 v[140:141], 11, v[140:141]
	v_lshl_add_u64 v[168:169], v[164:165], 0, v[140:141]
	ds_read_b128 v[140:143], v173 offset:59136
	s_waitcnt lgkmcnt(1)
	global_store_dwordx4 v[168:169], v[136:139], off
	s_nop 1
	v_add_u32_e32 v136, 0xd0, v166
	v_ashrrev_i32_e32 v137, 31, v136
	v_lshlrev_b64 v[136:137], 11, v[136:137]
	v_lshl_add_u64 v[136:137], v[164:165], 0, v[136:137]
	s_waitcnt lgkmcnt(0)
	global_store_dwordx4 v[136:137], v[140:143], off
	ds_read_b128 v[136:139], v128 offset:59136
	s_nop 0
	v_add_u32_e32 v140, 0xe0, v166
	v_ashrrev_i32_e32 v141, 31, v140
	v_lshlrev_b64 v[140:141], 11, v[140:141]
	v_lshl_add_u64 v[168:169], v[164:165], 0, v[140:141]
	ds_read_b128 v[140:143], v174 offset:59136
	s_waitcnt lgkmcnt(1)
	global_store_dwordx4 v[168:169], v[136:139], off
	s_nop 1
	v_add_u32_e32 v136, 0xf0, v166
	v_ashrrev_i32_e32 v137, 31, v136
	v_lshlrev_b64 v[136:137], 11, v[136:137]
	v_lshl_add_u64 v[136:137], v[164:165], 0, v[136:137]
	s_waitcnt lgkmcnt(0)
	global_store_dwordx4 v[136:137], v[140:143], off
